# grid barrier: poll loop without s_sleep (the arrival counter is re-read as soon as the previous read returns)
# baseline (speedup 1.0000x reference)
.Lxb_spin:
	global_load_dword v6, v32, s[4:5] sc1
	s_waitcnt vmcnt(0)
	v_sub_u32_e32 v6, v6, v4
	v_cmp_gt_i32_e32 vcc, 0, v6
	s_cbranch_vccz .Lxb_done
	s_add_i32 s16, s16, 1
	s_and_b32 s12, s16, 0xff
	s_cmp_lg_u32 s12, 0
	s_cbranch_scc1 .Lxb_spin
	global_load_dword v6, v32, s[64:65] sc1
	s_waitcnt vmcnt(0)
	v_cmp_ne_u32_e32 vcc, 0, v6
	s_cbranch_vccnz .Lxb_done
	s_cmp_lt_u32 s16, 0x40001
	s_cbranch_scc1 .Lxb_spin
	global_atomic_add v32, v188, s[64:65]
